# rwkv_post: carried-state correction S_start.z of each wave's 32 tokens on f32 matrix cores (v_mfma_f32_32x32x2_f32) via per-wave LDS tile, replaces readlane+pk_fma chains
# speedup vs baseline: 1.0061x; 1.0061x over previous
.LBB0_171:
	v_mov_b32_e32 v0, s15
	s_movk_i32 s6, 0x104
	v_and_b32_e32 v218, 31, v65
	v_and_b32_e32 v219, 32, v65
	v_mad_u32_u24 v218, v218, s6, v0
	v_lshl_add_u32 v218, v219, 2, v218
	v_add_u32_e32 v219, 0x2080, v218
	s_waitcnt lgkmcnt(0)
	s_barrier
	ds_read2_b32 v[0:1], v218 offset0:0 offset1:1
	ds_read2_b32 v[2:3], v218 offset0:2 offset1:3
	ds_read2_b32 v[4:5], v218 offset0:4 offset1:5
	ds_read2_b32 v[6:7], v218 offset0:6 offset1:7
	ds_read2_b32 v[8:9], v218 offset0:8 offset1:9
	ds_read2_b32 v[10:11], v218 offset0:10 offset1:11
	ds_read2_b32 v[12:13], v218 offset0:12 offset1:13
	ds_read2_b32 v[14:15], v218 offset0:14 offset1:15
	ds_read2_b32 v[16:17], v218 offset0:16 offset1:17
	ds_read2_b32 v[18:19], v218 offset0:18 offset1:19
	ds_read2_b32 v[20:21], v218 offset0:20 offset1:21
	ds_read2_b32 v[22:23], v218 offset0:22 offset1:23
	ds_read2_b32 v[24:25], v218 offset0:24 offset1:25
	ds_read2_b32 v[26:27], v218 offset0:26 offset1:27
	ds_read2_b32 v[28:29], v218 offset0:28 offset1:29
	ds_read2_b32 v[30:31], v218 offset0:30 offset1:31
	ds_read2_b32 v[32:33], v219 offset0:0 offset1:1
	ds_read2_b32 v[34:35], v219 offset0:2 offset1:3
	ds_read2_b32 v[36:37], v219 offset0:4 offset1:5
	ds_read2_b32 v[38:39], v219 offset0:6 offset1:7
	ds_read2_b32 v[40:41], v219 offset0:8 offset1:9
	ds_read2_b32 v[42:43], v219 offset0:10 offset1:11
	ds_read2_b32 v[44:45], v219 offset0:12 offset1:13
	ds_read2_b32 v[46:47], v219 offset0:14 offset1:15
	ds_read2_b32 v[48:49], v219 offset0:16 offset1:17
	ds_read2_b32 v[50:51], v219 offset0:18 offset1:19
	ds_read2_b32 v[52:53], v219 offset0:20 offset1:21
	ds_read2_b32 v[54:55], v219 offset0:22 offset1:23
	ds_read2_b32 v[56:57], v219 offset0:24 offset1:25
	ds_read2_b32 v[58:59], v219 offset0:26 offset1:27
	ds_read2_b32 v[60:61], v219 offset0:28 offset1:29
	ds_read2_b32 v[62:63], v219 offset0:30 offset1:31
.LBB0_172:
	s_waitcnt lgkmcnt(0)
	s_load_dwordx2 s[6:7], s[0:1], 0x80
	v_lshl_or_b32 v72, s11, 6, v65
	v_readlane_b32 s14, v255, 27
	v_readlane_b32 s15, v255, 28
	v_ashrrev_i32_e32 v64, 1, v64
	v_or_b32_e32 v66, s14, v72
	v_ashrrev_i32_e32 v67, 31, v66
	v_lshlrev_b64 v[66:67], 2, v[66:67]
	s_waitcnt lgkmcnt(0)
	v_lshl_add_u64 v[68:69], s[6:7], 0, v[66:67]
	global_load_dword v102, v[68:69], off
	s_load_dwordx2 s[6:7], s[0:1], 0x88
	v_and_b32_e32 v70, 0xffffffe0, v64
	s_lshl_b32 s11, s2, 17
	v_ashrrev_i32_e32 v71, 31, v70
	s_and_b32 s38, s11, 0x1f00000
	s_waitcnt lgkmcnt(0)
	v_lshl_add_u64 v[68:69], s[6:7], 0, v[66:67]
	global_load_dword v65, v[68:69], off
	s_load_dwordx2 s[6:7], s[0:1], 0x90
	s_lshl_b32 s2, s2, 16
	v_lshlrev_b32_e32 v168, 2, v72
	s_waitcnt lgkmcnt(0)
	v_lshl_add_u64 v[66:67], s[6:7], 0, v[66:67]
	global_load_dword v103, v[66:67], off
	s_load_dwordx2 s[6:7], s[0:1], 0x150
	s_load_dwordx2 s[14:15], s[0:1], 0x150
	s_load_dwordx2 s[16:17], s[0:1], 0x150
	s_load_dwordx2 s[18:19], s[0:1], 0x150
	s_load_dwordx2 s[20:21], s[0:1], 0x150
	s_load_dwordx2 s[22:23], s[0:1], 0x150
	s_load_dwordx2 s[24:25], s[0:1], 0x150
	v_lshlrev_b64 v[66:67], 12, v[70:71]
	v_lshl_add_u64 v[66:67], s[38:39], 0, v[66:67]
	v_lshl_or_b32 v66, v72, 1, v66
	s_and_b32 s38, s2, 0xf80000
	s_waitcnt lgkmcnt(0)
	v_lshl_add_u64 v[66:67], s[24:25], 0, v[66:67]
	s_mov_b64 s[24:25], 0xb643800
	v_lshlrev_b64 v[70:71], 11, v[70:71]
	v_lshl_add_u64 v[66:67], v[66:67], 0, s[24:25]
	v_lshl_add_u64 v[68:69], s[22:23], 0, v[168:169]
	v_lshl_add_u64 v[70:71], s[38:39], 0, v[70:71]
	v_lshl_add_u64 v[72:73], s[20:21], 0, v[168:169]
	v_lshl_add_u64 v[74:75], s[18:19], 0, v[168:169]
	v_lshl_add_u64 v[76:77], s[16:17], 0, v[168:169]
	v_lshl_add_u64 v[78:79], s[14:15], 0, v[168:169]
	v_lshl_add_u64 v[80:81], s[6:7], 0, v[168:169]
	v_lshrrev_b32_e32 v220, 6, v226
	v_and_b32_e32 v221, 63, v226
	v_lshlrev_b32_e32 v220, 13, v220
	v_lshl_add_u32 v220, v221, 2, v220
	v_add_u32_e32 v220, 0xc800, v220
	s_andn2_b64 vcc, exec, s[4:5]
	s_cbranch_vccnz .Lrp_nomm
	v_lshl_add_u64 v[208:209], v[78:79], 0, v[70:71]
	v_and_b32_e32 v210, 31, v221
	v_and_b32_e32 v211, 32, v221
	v_lshlrev_b32_e32 v210, 11, v210
	v_lshl_add_u32 v210, v211, 2, v210
	v_lshlrev_b32_e32 v211, 2, v221
	v_sub_u32_e32 v210, v210, v211
	v_mov_b32_e32 v211, 0
	v_lshl_add_u64 v[208:209], v[208:209], 0, v[210:211]
	v_add_co_u32_e32 v208, vcc, 0x2dd81000, v208
	s_nop 1
	v_addc_co_u32_e32 v209, vcc, 0, v209, vcc
	global_load_dwordx4 v[176:179], v[208:209], off offset:2048
	global_load_dwordx4 v[180:183], v[208:209], off offset:2064
	global_load_dwordx4 v[184:187], v[208:209], off offset:2080
	global_load_dwordx4 v[188:191], v[208:209], off offset:2096
	global_load_dwordx4 v[192:195], v[208:209], off offset:2112
	global_load_dwordx4 v[196:199], v[208:209], off offset:2128
	global_load_dwordx4 v[200:203], v[208:209], off offset:2144
	global_load_dwordx4 v[204:207], v[208:209], off offset:2160
	s_waitcnt vmcnt(0)
	v_mfma_f32_32x32x2_f32 v[120:135], v176, v0, 0
	v_mfma_f32_32x32x2_f32 v[136:151], v176, v32, 0
	v_mfma_f32_32x32x2_f32 v[120:135], v177, v1, v[120:135]
	v_mfma_f32_32x32x2_f32 v[136:151], v177, v33, v[136:151]
	v_mfma_f32_32x32x2_f32 v[120:135], v178, v2, v[120:135]
	v_mfma_f32_32x32x2_f32 v[136:151], v178, v34, v[136:151]
	v_mfma_f32_32x32x2_f32 v[120:135], v179, v3, v[120:135]
	v_mfma_f32_32x32x2_f32 v[136:151], v179, v35, v[136:151]
	v_mfma_f32_32x32x2_f32 v[120:135], v180, v4, v[120:135]
	v_mfma_f32_32x32x2_f32 v[136:151], v180, v36, v[136:151]
	v_mfma_f32_32x32x2_f32 v[120:135], v181, v5, v[120:135]
	v_mfma_f32_32x32x2_f32 v[136:151], v181, v37, v[136:151]
	v_mfma_f32_32x32x2_f32 v[120:135], v182, v6, v[120:135]
	v_mfma_f32_32x32x2_f32 v[136:151], v182, v38, v[136:151]
	v_mfma_f32_32x32x2_f32 v[120:135], v183, v7, v[120:135]
	v_mfma_f32_32x32x2_f32 v[136:151], v183, v39, v[136:151]
	v_mfma_f32_32x32x2_f32 v[120:135], v184, v8, v[120:135]
	v_mfma_f32_32x32x2_f32 v[136:151], v184, v40, v[136:151]
	v_mfma_f32_32x32x2_f32 v[120:135], v185, v9, v[120:135]
	v_mfma_f32_32x32x2_f32 v[136:151], v185, v41, v[136:151]
	v_mfma_f32_32x32x2_f32 v[120:135], v186, v10, v[120:135]
	v_mfma_f32_32x32x2_f32 v[136:151], v186, v42, v[136:151]
	v_mfma_f32_32x32x2_f32 v[120:135], v187, v11, v[120:135]
	v_mfma_f32_32x32x2_f32 v[136:151], v187, v43, v[136:151]
	v_mfma_f32_32x32x2_f32 v[120:135], v188, v12, v[120:135]
	v_mfma_f32_32x32x2_f32 v[136:151], v188, v44, v[136:151]
	v_mfma_f32_32x32x2_f32 v[120:135], v189, v13, v[120:135]
	v_mfma_f32_32x32x2_f32 v[136:151], v189, v45, v[136:151]
	v_mfma_f32_32x32x2_f32 v[120:135], v190, v14, v[120:135]
	v_mfma_f32_32x32x2_f32 v[136:151], v190, v46, v[136:151]
	v_mfma_f32_32x32x2_f32 v[120:135], v191, v15, v[120:135]
	v_mfma_f32_32x32x2_f32 v[136:151], v191, v47, v[136:151]
	v_mfma_f32_32x32x2_f32 v[120:135], v192, v16, v[120:135]
	v_mfma_f32_32x32x2_f32 v[136:151], v192, v48, v[136:151]
	v_mfma_f32_32x32x2_f32 v[120:135], v193, v17, v[120:135]
	v_mfma_f32_32x32x2_f32 v[136:151], v193, v49, v[136:151]
	v_mfma_f32_32x32x2_f32 v[120:135], v194, v18, v[120:135]
	v_mfma_f32_32x32x2_f32 v[136:151], v194, v50, v[136:151]
	v_mfma_f32_32x32x2_f32 v[120:135], v195, v19, v[120:135]
	v_mfma_f32_32x32x2_f32 v[136:151], v195, v51, v[136:151]
	v_mfma_f32_32x32x2_f32 v[120:135], v196, v20, v[120:135]
	v_mfma_f32_32x32x2_f32 v[136:151], v196, v52, v[136:151]
	v_mfma_f32_32x32x2_f32 v[120:135], v197, v21, v[120:135]
	v_mfma_f32_32x32x2_f32 v[136:151], v197, v53, v[136:151]
	v_mfma_f32_32x32x2_f32 v[120:135], v198, v22, v[120:135]
	v_mfma_f32_32x32x2_f32 v[136:151], v198, v54, v[136:151]
	v_mfma_f32_32x32x2_f32 v[120:135], v199, v23, v[120:135]
	v_mfma_f32_32x32x2_f32 v[136:151], v199, v55, v[136:151]
	v_mfma_f32_32x32x2_f32 v[120:135], v200, v24, v[120:135]
	v_mfma_f32_32x32x2_f32 v[136:151], v200, v56, v[136:151]
	v_mfma_f32_32x32x2_f32 v[120:135], v201, v25, v[120:135]
	v_mfma_f32_32x32x2_f32 v[136:151], v201, v57, v[136:151]
	v_mfma_f32_32x32x2_f32 v[120:135], v202, v26, v[120:135]
	v_mfma_f32_32x32x2_f32 v[136:151], v202, v58, v[136:151]
	v_mfma_f32_32x32x2_f32 v[120:135], v203, v27, v[120:135]
	v_mfma_f32_32x32x2_f32 v[136:151], v203, v59, v[136:151]
	v_mfma_f32_32x32x2_f32 v[120:135], v204, v28, v[120:135]
	v_mfma_f32_32x32x2_f32 v[136:151], v204, v60, v[136:151]
	v_mfma_f32_32x32x2_f32 v[120:135], v205, v29, v[120:135]
	v_mfma_f32_32x32x2_f32 v[136:151], v205, v61, v[136:151]
	v_mfma_f32_32x32x2_f32 v[120:135], v206, v30, v[120:135]
	v_mfma_f32_32x32x2_f32 v[136:151], v206, v62, v[136:151]
	v_mfma_f32_32x32x2_f32 v[120:135], v207, v31, v[120:135]
	v_mfma_f32_32x32x2_f32 v[136:151], v207, v63, v[136:151]
	s_nop 7
	s_nop 7
	s_nop 3
	v_permlane32_swap_b32_e32 v120, v136
	v_permlane32_swap_b32_e32 v121, v137
	v_permlane32_swap_b32_e32 v122, v138
	v_permlane32_swap_b32_e32 v123, v139
	v_permlane32_swap_b32_e32 v124, v140
	v_permlane32_swap_b32_e32 v125, v141
	v_permlane32_swap_b32_e32 v126, v142
	v_permlane32_swap_b32_e32 v127, v143
	v_permlane32_swap_b32_e32 v128, v144
	v_permlane32_swap_b32_e32 v129, v145
	v_permlane32_swap_b32_e32 v130, v146
	v_permlane32_swap_b32_e32 v131, v147
	v_permlane32_swap_b32_e32 v132, v148
	v_permlane32_swap_b32_e32 v133, v149
	v_permlane32_swap_b32_e32 v134, v150
	v_permlane32_swap_b32_e32 v135, v151
	s_nop 1
	ds_write_b32 v220, v120
	ds_write_b32 v220, v121 offset:256
	ds_write_b32 v220, v122 offset:512
	ds_write_b32 v220, v123 offset:768
	ds_write_b32 v220, v136 offset:1024
	ds_write_b32 v220, v137 offset:1280
	ds_write_b32 v220, v138 offset:1536
	ds_write_b32 v220, v139 offset:1792
	s_waitcnt lgkmcnt(4)
	ds_write_b32 v220, v124 offset:2048
	ds_write_b32 v220, v125 offset:2304
	ds_write_b32 v220, v126 offset:2560
	ds_write_b32 v220, v127 offset:2816
	ds_write_b32 v220, v140 offset:3072
	ds_write_b32 v220, v141 offset:3328
	ds_write_b32 v220, v142 offset:3584
	ds_write_b32 v220, v143 offset:3840
	s_waitcnt lgkmcnt(4)
	ds_write_b32 v220, v128 offset:4096
	ds_write_b32 v220, v129 offset:4352
	ds_write_b32 v220, v130 offset:4608
	ds_write_b32 v220, v131 offset:4864
	ds_write_b32 v220, v144 offset:5120
	ds_write_b32 v220, v145 offset:5376
	ds_write_b32 v220, v146 offset:5632
	ds_write_b32 v220, v147 offset:5888
	s_waitcnt lgkmcnt(4)
	ds_write_b32 v220, v132 offset:6144
	ds_write_b32 v220, v133 offset:6400
	ds_write_b32 v220, v134 offset:6656
	ds_write_b32 v220, v135 offset:6912
	ds_write_b32 v220, v148 offset:7168
	ds_write_b32 v220, v149 offset:7424
	ds_write_b32 v220, v150 offset:7680
	ds_write_b32 v220, v151 offset:7936
	s_waitcnt lgkmcnt(4)
.Lrp_nomm:
	s_mov_b32 s2, -4
	s_branch .LBB0_174
.LBB0_173:
	v_add_u32_e32 v220, 0x400, v220
	s_waitcnt vmcnt(7)
	v_add_f32_dpp v64, v84, v84 quad_perm:[1,0,3,2] row_mask:0xf bank_mask:0xf bound_ctrl:1
	s_waitcnt vmcnt(5)
	v_mul_f32_e32 v83, v83, v98
	s_add_i32 s2, s2, 4
	v_add_f32_dpp v64, v64, v64 quad_perm:[2,3,0,1] row_mask:0xf bank_mask:0xf bound_ctrl:1
	s_cmp_lt_u32 s2, 28
	s_nop 0
	v_add_f32_dpp v64, v64, v64 row_half_mirror row_mask:0xf bank_mask:0xf bound_ctrl:1
	s_nop 1
	v_add_f32_dpp v64, v64, v64 row_mirror row_mask:0xf bank_mask:0xf bound_ctrl:1
	s_nop 0
	v_readlane_b32 s11, v64, 16
	v_readlane_b32 s14, v64, 48
	v_readlane_b32 s6, v64, 0
	v_readlane_b32 s7, v64, 32
	v_mov_b32_e32 v86, s11
	v_mov_b32_e32 v87, s14
	v_pk_add_f32 v[86:87], s[6:7], v[86:87]
	s_nop 0
	v_add_f32_e32 v64, v86, v87
	v_fmac_f32_e32 v84, 0xbc800000, v64
	v_mul_f32_e32 v64, v84, v84
	s_nop 1
	v_mov_b32_dpp v64, v64 quad_perm:[1,0,3,2] row_mask:0xf bank_mask:0xf bound_ctrl:1
	v_fmac_f32_e32 v64, v84, v84
	s_nop 1
	v_add_f32_dpp v64, v64, v64 quad_perm:[2,3,0,1] row_mask:0xf bank_mask:0xf bound_ctrl:1
	s_nop 1
	v_add_f32_dpp v64, v64, v64 row_half_mirror row_mask:0xf bank_mask:0xf bound_ctrl:1
	s_nop 1
	v_add_f32_dpp v64, v64, v64 row_mirror row_mask:0xf bank_mask:0xf bound_ctrl:1
	s_nop 0
	v_readlane_b32 s11, v64, 16
	v_readlane_b32 s14, v64, 48
	v_readlane_b32 s6, v64, 0
	v_readlane_b32 s7, v64, 32
	v_mov_b32_e32 v86, s11
	v_mov_b32_e32 v87, s14
	v_pk_add_f32 v[86:87], s[6:7], v[86:87]
	s_nop 0
	v_add_f32_e32 v64, v86, v87
	v_fmamk_f32 v64, v64, 0x3c800000, v230
	v_mul_f32_e32 v85, 0x4b800000, v64
	v_cmp_gt_f32_e32 vcc, s29, v64
	s_nop 1
	v_cndmask_b32_e32 v64, v64, v85, vcc
	v_rsq_f32_e32 v64, v64
	s_nop 0
	v_mul_f32_e32 v85, 0x45800000, v64
	v_cndmask_b32_e32 v64, v64, v85, vcc
	v_mul_f32_e32 v64, v84, v64
	v_mul_f32_e32 v84, v102, v83
	s_nop 1
	v_mov_b32_dpp v84, v84 quad_perm:[1,0,3,2] row_mask:0xf bank_mask:0xf bound_ctrl:1
	v_fmac_f32_e32 v84, v102, v83
	s_nop 1
	v_add_f32_dpp v83, v84, v84 quad_perm:[2,3,0,1] row_mask:0xf bank_mask:0xf bound_ctrl:1
	s_nop 1
	v_add_f32_dpp v83, v83, v83 row_half_mirror row_mask:0xf bank_mask:0xf bound_ctrl:1
	s_nop 1
	v_add_f32_dpp v83, v83, v83 row_mirror row_mask:0xf bank_mask:0xf bound_ctrl:1
	s_nop 0
	v_readlane_b32 s11, v83, 16
	v_readlane_b32 s14, v83, 48
	v_readlane_b32 s6, v83, 0
	v_readlane_b32 s7, v83, 32
	v_mov_b32_e32 v84, s11
	v_mov_b32_e32 v85, s14
	v_pk_add_f32 v[84:85], s[6:7], v[84:85]
	v_mov_b32_e32 v83, v65
	v_pk_add_f32 v[84:85], v[84:85], v[84:85] op_sel:[0,1] op_sel_hi:[1,0]
	s_mov_b64 s[6:7], 0x2000
	v_mov_b32_e32 v85, v64
	s_waitcnt vmcnt(4)
	v_pk_mul_f32 v[82:83], v[82:83], v[84:85]
	v_lshl_add_u64 v[70:71], v[70:71], 0, s[6:7]
	v_add_f32_e32 v64, v103, v83
	v_add_f32_e32 v64, v82, v64
	s_waitcnt vmcnt(3)
	v_mul_f32_e32 v64, v94, v64
	v_bfe_u32 v82, v64, 16, 1
	v_add3_u32 v64, v64, v82, s43
	global_store_short_d16_hi v[66:67], v64, off
	v_lshl_add_u64 v[66:67], v[66:67], 0, s[40:41]
	s_cbranch_scc0 .LBB0_190
.LBB0_174:
	ds_read_b32 v216, v220
	ds_read_b32 v217, v220 offset:256
	ds_read_b32 v218, v220 offset:512
	ds_read_b32 v219, v220 offset:768
	v_lshl_add_u64 v[84:85], v[80:81], 0, v[70:71]
	v_add_co_u32_e32 v82, vcc, 0x27640000, v84
	v_cndmask_b32_e64 v64, 0, 1, s[4:5]
	s_nop 0
	v_addc_co_u32_e32 v83, vcc, 0, v85, vcc
	global_load_dword v168, v[82:83], off
	v_mov_b32_e32 v109, 0
	v_cmp_ne_u32_e64 s[6:7], 1, v64
	s_andn2_b64 vcc, exec, s[4:5]
	v_lshl_add_u64 v[82:83], v[78:79], 0, v[70:71]
	v_mov_b32_e32 v112, 0
	s_cbranch_vccnz .LBB0_176
	v_add_co_u32_e32 v86, vcc, 0x2dd81000, v82
	s_nop 1
	v_addc_co_u32_e32 v87, vcc, 0, v83, vcc
.LBB0_176:
	v_lshl_add_u64 v[100:101], v[76:77], 0, v[70:71]
	v_add_co_u32_e32 v86, vcc, 0x20640000, v100
	v_lshl_add_u64 v[98:99], v[74:75], 0, v[70:71]
	s_nop 0
	v_addc_co_u32_e32 v87, vcc, 0, v101, vcc
	global_load_dword v110, v[86:87], off
	v_add_co_u32_e32 v86, vcc, 0x21640000, v98
	v_lshl_add_u64 v[96:97], v[72:73], 0, v[70:71]
	s_nop 0
	v_addc_co_u32_e32 v87, vcc, 0, v99, vcc
	global_load_dword v111, v[86:87], off
	v_add_co_u32_e32 v86, vcc, 0x22640000, v96
	v_lshl_add_u64 v[94:95], v[68:69], 0, v[70:71]
	s_nop 0
	v_addc_co_u32_e32 v87, vcc, 0, v97, vcc
	global_load_dword v64, v[86:87], off
	v_add_co_u32_e32 v86, vcc, 0x26640000, v94
	s_nop 1
	v_addc_co_u32_e32 v87, vcc, 0, v95, vcc
	global_load_dword v93, v[86:87], off
	v_add_co_u32_e32 v86, vcc, 0x27640000, v84
	s_nop 1
	v_addc_co_u32_e32 v87, vcc, 0, v85, vcc
	global_load_dword v92, v[86:87], off offset:2048
	s_and_b64 vcc, exec, s[6:7]
	s_cbranch_vccnz .LBB0_178
	v_add_co_u32_e32 v86, vcc, 0x2dd82000, v82
	s_nop 1
	v_addc_co_u32_e32 v87, vcc, 0, v83, vcc
.LBB0_178:
	v_add_co_u32_e32 v86, vcc, 0x20640000, v100
	v_mov_b32_e32 v104, 0
	s_nop 0
	v_addc_co_u32_e32 v87, vcc, 0, v101, vcc
	global_load_dword v89, v[86:87], off offset:2048
	v_add_co_u32_e32 v86, vcc, 0x21640000, v98
	v_mov_b32_e32 v107, 0
	s_nop 0
	v_addc_co_u32_e32 v87, vcc, 0, v99, vcc
	global_load_dword v91, v[86:87], off offset:2048
	v_add_co_u32_e32 v86, vcc, 0x22640000, v96
	s_nop 1
	v_addc_co_u32_e32 v87, vcc, 0, v97, vcc
	global_load_dword v90, v[86:87], off offset:2048
	v_add_co_u32_e32 v86, vcc, 0x26640000, v94
	s_nop 1
	v_addc_co_u32_e32 v87, vcc, 0, v95, vcc
	global_load_dword v108, v[86:87], off offset:2048
	v_add_co_u32_e32 v86, vcc, 0x27641000, v84
	s_nop 1
	v_addc_co_u32_e32 v87, vcc, 0, v85, vcc
	global_load_dword v88, v[86:87], off
	s_and_b64 vcc, exec, s[6:7]
	s_cbranch_vccnz .LBB0_180
	v_add_co_u32_e32 v86, vcc, 0x2dd82000, v82
	s_nop 1
	v_addc_co_u32_e32 v87, vcc, 0, v83, vcc
.LBB0_180:
	v_add_co_u32_e32 v86, vcc, 0x20641000, v100
	s_nop 1
	v_addc_co_u32_e32 v87, vcc, 0, v101, vcc
	v_add_co_u32_e32 v114, vcc, 0x21641000, v98
	global_load_dword v87, v[86:87], off
	s_nop 0
	v_addc_co_u32_e32 v115, vcc, 0, v99, vcc
	global_load_dword v106, v[114:115], off
	v_add_co_u32_e32 v114, vcc, 0x22641000, v96
	s_nop 1
	v_addc_co_u32_e32 v115, vcc, 0, v97, vcc
	global_load_dword v86, v[114:115], off
	v_add_co_u32_e32 v114, vcc, 0x26641000, v94
	s_nop 1
	v_addc_co_u32_e32 v115, vcc, 0, v95, vcc
	v_add_co_u32_e32 v84, vcc, 0x27641000, v84
	global_load_dword v105, v[114:115], off
	s_nop 0
	v_addc_co_u32_e32 v85, vcc, 0, v85, vcc
	global_load_dword v84, v[84:85], off offset:2048
	s_and_b64 vcc, exec, s[6:7]
	s_cbranch_vccnz .LBB0_182
	v_add_co_u32_e32 v82, vcc, 0x2dd83000, v82
	s_nop 1
	v_addc_co_u32_e32 v83, vcc, 0, v83, vcc
.LBB0_182:
	v_add_co_u32_e32 v82, vcc, 0x20641000, v100
	s_nop 1
	v_addc_co_u32_e32 v83, vcc, 0, v101, vcc
	v_add_co_u32_e32 v98, vcc, 0x21641000, v98
	global_load_dword v83, v[82:83], off offset:2048
	s_nop 0
	v_addc_co_u32_e32 v99, vcc, 0, v99, vcc
	v_add_co_u32_e32 v96, vcc, 0x22641000, v96
	global_load_dword v98, v[98:99], off offset:2048
	s_nop 0
	v_addc_co_u32_e32 v97, vcc, 0, v97, vcc
	v_add_co_u32_e32 v94, vcc, 0x26641000, v94
	global_load_dword v82, v[96:97], off offset:2048
	s_nop 0
	v_addc_co_u32_e32 v95, vcc, 0, v95, vcc
	global_load_dword v94, v[94:95], off offset:2048
	s_and_b64 vcc, exec, s[6:7]
	s_cbranch_vccnz .LBB0_184
	s_waitcnt vmcnt(0) lgkmcnt(0)
	v_add_f32_e32 v168, v168, v216
.LBB0_184:
	s_waitcnt vmcnt(0)
	s_nop 0
	v_add_f32_dpp v85, v168, v168 quad_perm:[1,0,3,2] row_mask:0xf bank_mask:0xf bound_ctrl:1
	s_nop 1
	v_add_f32_dpp v85, v85, v85 quad_perm:[2,3,0,1] row_mask:0xf bank_mask:0xf bound_ctrl:1
	s_nop 1
	v_add_f32_dpp v85, v85, v85 row_half_mirror row_mask:0xf bank_mask:0xf bound_ctrl:1
	s_nop 1
	v_add_f32_dpp v85, v85, v85 row_mirror row_mask:0xf bank_mask:0xf bound_ctrl:1
	s_nop 0
	v_readlane_b32 s11, v85, 16
	v_readlane_b32 s16, v85, 48
	v_readlane_b32 s14, v85, 0
	v_readlane_b32 s15, v85, 32
	v_mov_b32_e32 v96, s11
	v_mov_b32_e32 v97, s16
	v_pk_add_f32 v[96:97], s[14:15], v[96:97]
	s_nop 0
	v_add_f32_e32 v85, v96, v97
	v_fmac_f32_e32 v168, 0xbc800000, v85
	v_mul_f32_e32 v85, v168, v168
	s_nop 1
	v_mov_b32_dpp v85, v85 quad_perm:[1,0,3,2] row_mask:0xf bank_mask:0xf bound_ctrl:1
	v_fmac_f32_e32 v85, v168, v168
	s_nop 1
	v_add_f32_dpp v85, v85, v85 quad_perm:[2,3,0,1] row_mask:0xf bank_mask:0xf bound_ctrl:1
	s_nop 1
	v_add_f32_dpp v85, v85, v85 row_half_mirror row_mask:0xf bank_mask:0xf bound_ctrl:1
	s_nop 1
	v_add_f32_dpp v85, v85, v85 row_mirror row_mask:0xf bank_mask:0xf bound_ctrl:1
	s_nop 0
	v_readlane_b32 s11, v85, 16
	v_readlane_b32 s16, v85, 48
	v_readlane_b32 s14, v85, 0
	v_readlane_b32 s15, v85, 32
	v_mov_b32_e32 v96, s11
	v_mov_b32_e32 v97, s16
	v_pk_add_f32 v[96:97], s[14:15], v[96:97]
	s_nop 0
	v_add_f32_e32 v85, v96, v97
	v_fmamk_f32 v85, v85, 0x3c800000, v230
	v_mul_f32_e32 v95, 0x4b800000, v85
	v_cmp_gt_f32_e32 vcc, s29, v85
	s_nop 1
	v_cndmask_b32_e32 v85, v85, v95, vcc
	v_rsq_f32_e32 v85, v85
	s_nop 0
	v_mul_f32_e32 v95, 0x45800000, v85
	v_cndmask_b32_e32 v85, v85, v95, vcc
	s_waitcnt vmcnt(17)
	v_mul_f32_e32 v95, v110, v111
	v_mul_f32_e32 v96, v102, v95
	v_mul_f32_e32 v85, v168, v85
	s_nop 0
	v_mov_b32_dpp v96, v96 quad_perm:[1,0,3,2] row_mask:0xf bank_mask:0xf bound_ctrl:1
	v_fmac_f32_e32 v96, v102, v95
	s_nop 1
	v_add_f32_dpp v95, v96, v96 quad_perm:[2,3,0,1] row_mask:0xf bank_mask:0xf bound_ctrl:1
	s_nop 1
	v_add_f32_dpp v95, v95, v95 row_half_mirror row_mask:0xf bank_mask:0xf bound_ctrl:1
	s_nop 1
	v_add_f32_dpp v95, v95, v95 row_mirror row_mask:0xf bank_mask:0xf bound_ctrl:1
	s_nop 0
	v_readlane_b32 s11, v95, 16
	v_readlane_b32 s16, v95, 48
	v_readlane_b32 s14, v95, 0
	v_readlane_b32 s15, v95, 32
	v_mov_b32_e32 v96, s11
	v_mov_b32_e32 v97, s16
	v_pk_add_f32 v[96:97], s[14:15], v[96:97]
	s_nop 0
	v_pk_add_f32 v[96:97], v[96:97], v[96:97] op_sel:[0,1] op_sel_hi:[1,0]
	s_nop 0
	v_mov_b32_e32 v97, v85
	s_waitcnt vmcnt(16)
	v_pk_mul_f32 v[96:97], v[64:65], v[96:97]
	s_nop 0
	v_add_f32_e32 v64, v103, v97
	v_add_f32_e32 v64, v96, v64
	s_waitcnt vmcnt(15)
	v_mul_f32_e32 v64, v93, v64
	v_add_co_u32_e32 v96, vcc, 0xffffd000, v66
	v_bfe_u32 v85, v64, 16, 1
	s_nop 0
	v_addc_co_u32_e32 v97, vcc, -1, v67, vcc
	v_add3_u32 v64, v64, v85, s43
	s_and_b64 vcc, exec, s[6:7]
	global_store_short_d16_hi v[96:97], v64, off
	s_cbranch_vccnz .LBB0_186
	s_waitcnt vmcnt(15) lgkmcnt(0)
	v_add_f32_e32 v92, v92, v217
.LBB0_186:
	s_waitcnt vmcnt(15)
	s_nop 0
	v_add_f32_dpp v64, v92, v92 quad_perm:[1,0,3,2] row_mask:0xf bank_mask:0xf bound_ctrl:1
	s_nop 1
	v_add_f32_dpp v64, v64, v64 quad_perm:[2,3,0,1] row_mask:0xf bank_mask:0xf bound_ctrl:1
	s_nop 1
	v_add_f32_dpp v64, v64, v64 row_half_mirror row_mask:0xf bank_mask:0xf bound_ctrl:1
	s_nop 1
	v_add_f32_dpp v64, v64, v64 row_mirror row_mask:0xf bank_mask:0xf bound_ctrl:1
	s_nop 0
	v_readlane_b32 s11, v64, 16
	v_readlane_b32 s16, v64, 48
	v_readlane_b32 s14, v64, 0
	v_readlane_b32 s15, v64, 32
	v_mov_b32_e32 v96, s11
	v_mov_b32_e32 v97, s16
	v_pk_add_f32 v[96:97], s[14:15], v[96:97]
	s_nop 0
	v_add_f32_e32 v64, v96, v97
	v_fmac_f32_e32 v92, 0xbc800000, v64
	v_mul_f32_e32 v64, v92, v92
	s_nop 1
	v_mov_b32_dpp v64, v64 quad_perm:[1,0,3,2] row_mask:0xf bank_mask:0xf bound_ctrl:1
	v_fmac_f32_e32 v64, v92, v92
	s_nop 1
	v_add_f32_dpp v64, v64, v64 quad_perm:[2,3,0,1] row_mask:0xf bank_mask:0xf bound_ctrl:1
	s_nop 1
	v_add_f32_dpp v64, v64, v64 row_half_mirror row_mask:0xf bank_mask:0xf bound_ctrl:1
	s_nop 1
	v_add_f32_dpp v64, v64, v64 row_mirror row_mask:0xf bank_mask:0xf bound_ctrl:1
	s_nop 0
	v_readlane_b32 s11, v64, 16
	v_readlane_b32 s16, v64, 48
	v_readlane_b32 s14, v64, 0
	v_readlane_b32 s15, v64, 32
	v_mov_b32_e32 v96, s11
	v_mov_b32_e32 v97, s16
	v_pk_add_f32 v[96:97], s[14:15], v[96:97]
	s_nop 0
	v_add_f32_e32 v64, v96, v97
	v_fmamk_f32 v64, v64, 0x3c800000, v230
	v_mul_f32_e32 v85, 0x4b800000, v64
	v_cmp_gt_f32_e32 vcc, s29, v64
	s_nop 1
	v_cndmask_b32_e32 v64, v64, v85, vcc
	v_rsq_f32_e32 v64, v64
	s_nop 0
	v_mul_f32_e32 v85, 0x45800000, v64
	v_cndmask_b32_e32 v64, v64, v85, vcc
	s_waitcnt vmcnt(13)
	v_mul_f32_e32 v85, v89, v91
	v_mul_f32_e32 v89, v102, v85
	v_mul_f32_e32 v64, v92, v64
	v_mov_b32_e32 v91, v65
	v_mov_b32_dpp v89, v89 quad_perm:[1,0,3,2] row_mask:0xf bank_mask:0xf bound_ctrl:1
	v_fmac_f32_e32 v89, v102, v85
	s_nop 1
	v_add_f32_dpp v85, v89, v89 quad_perm:[2,3,0,1] row_mask:0xf bank_mask:0xf bound_ctrl:1
	s_nop 1
	v_add_f32_dpp v85, v85, v85 row_half_mirror row_mask:0xf bank_mask:0xf bound_ctrl:1
	s_nop 1
	v_add_f32_dpp v85, v85, v85 row_mirror row_mask:0xf bank_mask:0xf bound_ctrl:1
	s_nop 0
	v_readlane_b32 s11, v85, 16
	v_readlane_b32 s16, v85, 48
	v_readlane_b32 s14, v85, 0
	v_readlane_b32 s15, v85, 32
	v_mov_b32_e32 v92, s11
	v_mov_b32_e32 v93, s16
	v_pk_add_f32 v[92:93], s[14:15], v[92:93]
	s_nop 0
	v_pk_add_f32 v[92:93], v[92:93], v[92:93] op_sel:[0,1] op_sel_hi:[1,0]
	s_nop 0
	v_mov_b32_e32 v93, v64
	s_waitcnt vmcnt(12)
	v_pk_mul_f32 v[90:91], v[90:91], v[92:93]
	s_nop 0
	v_add_f32_e32 v64, v103, v91
	v_add_f32_e32 v64, v90, v64
	s_waitcnt vmcnt(11)
	v_mul_f32_e32 v64, v108, v64
	v_add_co_u32_e32 v90, vcc, 0xffffe000, v66
	v_bfe_u32 v85, v64, 16, 1
	s_nop 0
	v_addc_co_u32_e32 v91, vcc, -1, v67, vcc
	v_add3_u32 v64, v64, v85, s43
	s_and_b64 vcc, exec, s[6:7]
	global_store_short_d16_hi v[90:91], v64, off
	s_cbranch_vccnz .LBB0_188
	s_waitcnt vmcnt(11) lgkmcnt(0)
	v_add_f32_e32 v88, v88, v218
.LBB0_188:
	s_waitcnt vmcnt(11)
	s_nop 0
	v_add_f32_dpp v64, v88, v88 quad_perm:[1,0,3,2] row_mask:0xf bank_mask:0xf bound_ctrl:1
	s_nop 1
	v_add_f32_dpp v64, v64, v64 quad_perm:[2,3,0,1] row_mask:0xf bank_mask:0xf bound_ctrl:1
	s_nop 1
	v_add_f32_dpp v64, v64, v64 row_half_mirror row_mask:0xf bank_mask:0xf bound_ctrl:1
	s_nop 1
	v_add_f32_dpp v64, v64, v64 row_mirror row_mask:0xf bank_mask:0xf bound_ctrl:1
	s_nop 0
	v_readlane_b32 s11, v64, 16
	v_readlane_b32 s16, v64, 48
	v_readlane_b32 s14, v64, 0
	v_readlane_b32 s15, v64, 32
	v_mov_b32_e32 v90, s11
	v_mov_b32_e32 v91, s16
	v_pk_add_f32 v[90:91], s[14:15], v[90:91]
	s_nop 0
	v_add_f32_e32 v64, v90, v91
	v_fmac_f32_e32 v88, 0xbc800000, v64
	v_mul_f32_e32 v64, v88, v88
	s_nop 1
	v_mov_b32_dpp v64, v64 quad_perm:[1,0,3,2] row_mask:0xf bank_mask:0xf bound_ctrl:1
	v_fmac_f32_e32 v64, v88, v88
	s_nop 1
	v_add_f32_dpp v64, v64, v64 quad_perm:[2,3,0,1] row_mask:0xf bank_mask:0xf bound_ctrl:1
	s_nop 1
	v_add_f32_dpp v64, v64, v64 row_half_mirror row_mask:0xf bank_mask:0xf bound_ctrl:1
	s_nop 1
	v_add_f32_dpp v64, v64, v64 row_mirror row_mask:0xf bank_mask:0xf bound_ctrl:1
	s_nop 0
	v_readlane_b32 s11, v64, 16
	v_readlane_b32 s16, v64, 48
	v_readlane_b32 s14, v64, 0
	v_readlane_b32 s15, v64, 32
	v_mov_b32_e32 v90, s11
	v_mov_b32_e32 v91, s16
	v_pk_add_f32 v[90:91], s[14:15], v[90:91]
	s_nop 0
	v_add_f32_e32 v64, v90, v91
	v_fmamk_f32 v64, v64, 0x3c800000, v230
	v_mul_f32_e32 v85, 0x4b800000, v64
	v_cmp_gt_f32_e32 vcc, s29, v64
	s_nop 1
	v_cndmask_b32_e32 v64, v64, v85, vcc
	v_rsq_f32_e32 v64, v64
	s_nop 0
	v_mul_f32_e32 v85, 0x45800000, v64
	v_cndmask_b32_e32 v64, v64, v85, vcc
	s_waitcnt vmcnt(9)
	v_mul_f32_e32 v85, v87, v106
	v_mul_f32_e32 v87, v102, v85
	v_mul_f32_e32 v64, v88, v64
	s_and_b64 vcc, exec, s[6:7]
	v_mov_b32_dpp v87, v87 quad_perm:[1,0,3,2] row_mask:0xf bank_mask:0xf bound_ctrl:1
	v_fmac_f32_e32 v87, v102, v85
	s_nop 1
	v_add_f32_dpp v85, v87, v87 quad_perm:[2,3,0,1] row_mask:0xf bank_mask:0xf bound_ctrl:1
	v_mov_b32_e32 v87, v65
	s_nop 0
	v_add_f32_dpp v85, v85, v85 row_half_mirror row_mask:0xf bank_mask:0xf bound_ctrl:1
	s_nop 1
	v_add_f32_dpp v85, v85, v85 row_mirror row_mask:0xf bank_mask:0xf bound_ctrl:1
	s_nop 0
	v_readlane_b32 s11, v85, 16
	v_readlane_b32 s16, v85, 48
	v_readlane_b32 s14, v85, 0
	v_readlane_b32 s15, v85, 32
	v_mov_b32_e32 v88, s11
	v_mov_b32_e32 v89, s16
	v_pk_add_f32 v[88:89], s[14:15], v[88:89]
	s_nop 0
	v_pk_add_f32 v[88:89], v[88:89], v[88:89] op_sel:[0,1] op_sel_hi:[1,0]
	s_nop 0
	v_mov_b32_e32 v89, v64
	s_waitcnt vmcnt(8)
	v_pk_mul_f32 v[86:87], v[86:87], v[88:89]
	s_nop 0
	v_add_f32_e32 v64, v103, v87
	v_add_f32_e32 v64, v86, v64
	s_waitcnt vmcnt(7)
	v_mul_f32_e32 v64, v105, v64
	v_bfe_u32 v85, v64, 16, 1
	v_add3_u32 v64, v64, v85, s43
	global_store_short_d16_hi v[66:67], v64, off offset:-4096
	s_cbranch_vccnz .LBB0_173
	s_waitcnt vmcnt(7) lgkmcnt(0)
	v_add_f32_e32 v84, v84, v219
	s_branch .LBB0_173
